# w_down weight transposes moved out of phase 0 into the idle tail of the w_up GEMM phase (84 workgroups without a sixth unit)
# speedup vs baseline: 1.0076x; 1.0070x over previous
.LBB0_506:
	s_movk_i32 s32, 0x11c0
	v_readlane_b32 s0, v254, 62
	s_cmpk_lg_u32 s0, 0x100
	s_cbranch_scc1 .Ltp_bound
	s_movk_i32 s32, 0xf00
.Ltp_bound:
	v_readlane_b32 s0, v255, 2
	s_cmp_ge_i32 s0, s32
	s_waitcnt lgkmcnt(0)
	s_barrier
	v_readlane_b32 s1, v255, 3
	s_cbranch_scc1 .LBB0_716
	s_add_u32 s6, s18, 0x1e80000
	s_addc_u32 s7, s19, 0
	s_add_u32 s8, s18, 0x1380000
	s_addc_u32 s9, s19, 0
	s_add_u32 s10, s18, 0x1bd3d800
	v_ashrrev_i32_e32 v27, 3, v174
	v_lshlrev_b32_e32 v2, 3, v174
	s_addc_u32 s11, s19, 0
	s_waitcnt vmcnt(0)
	v_and_b32_e32 v36, 56, v2
	v_lshlrev_b32_e32 v2, 2, v174
	s_add_u32 s12, s18, 0x780000
	v_lshlrev_b32_e32 v4, 1, v27
	v_lshrrev_b32_e32 v5, 2, v27
	v_readlane_b32 s0, v254, 62
	v_and_b32_e32 v2, 60, v2
	s_addc_u32 s13, s19, 0
	v_and_b32_e32 v4, 24, v4
	v_and_b32_e32 v5, 4, v5
	v_and_b32_e32 v6, 35, v27
	v_readlane_b32 s1, v254, 63
	s_mov_b32 s2, s0
	s_lshl_b32 s34, s0, 2
	s_movk_i32 s0, 0x104
	v_lshl_add_u32 v3, v2, 2, 0
	v_or3_b32 v37, v5, v6, v4
	v_mul_lo_u32 v4, v1, s0
	v_mad_u32_u24 v48, v36, s0, 0
	v_readlane_b32 s0, v255, 2
	s_lshl_b32 s33, s0, 6
	s_lshl_b32 s35, s2, 8
	s_lshl_b32 s36, s0, 2
	s_lshl_b32 s37, s2, 4
	s_lshl_b32 s38, s2, 1
	s_lshl_b32 s39, s2, 7
	s_mul_i32 s40, s2, 0xc0
	s_mul_i32 s41, s2, 12
	s_lshl_b32 s42, s2, 6
	s_waitcnt vmcnt(12)
	v_lshlrev_b32_e32 v38, 2, v2
	v_add_u32_e32 v49, v3, v4
	s_mov_b32 s43, s0
	v_readlane_b32 s1, v255, 3
	s_branch .LBB0_510

.LBB0_509:
	s_add_i32 s43, s43, s34
	s_add_i32 s33, s33, s35
	s_add_i32 s36, s36, s37
	s_cmp_ge_i32 s43, s32
	s_barrier
	s_cbranch_scc1 .LBB0_716

.LBB0_535:
	v_readlane_b32 s0, v254, 62
	s_add_i32 s44, s0, s43
	s_cmp_lt_i32 s44, s32
	s_cselect_b64 s[22:23], -1, 0
	s_cmp_ge_i32 s44, s32
	v_readlane_b32 s1, v254, 63
	s_cbranch_scc1 .LBB0_561
	s_cmpk_lt_i32 s44, 0x380
	s_mov_b64 s[26:27], -1
	s_cbranch_scc1 .LBB0_555
	s_cmpk_lt_u32 s44, 0x580
	s_cbranch_scc1 .LBB0_548
	s_cmpk_lt_u32 s44, 0x980
	s_cbranch_scc1 .LBB0_543
	s_cmpk_lt_u32 s44, 0xf00
	s_mov_b64 s[0:1], -1
	s_cbranch_scc1 .LBB0_541
	v_readlane_b32 s0, v254, 56
	v_readlane_b32 s1, v254, 57
	s_load_dwordx2 s[2:3], s[0:1], 0xf0
	s_add_i32 s0, s34, s36
	s_and_b32 s0, s0, 0x7fffffc0
	s_add_i32 s25, s0, 0xffffc400
	s_add_i32 s0, s42, s33
	s_and_b32 s24, s0, 0x3c0
	s_mov_b64 s[0:1], 0

.LBB0_561:
	s_add_i32 s45, s38, s43
	s_cmp_lt_i32 s45, s32
	s_cselect_b64 s[24:25], -1, 0
	s_cmp_ge_i32 s45, s32
	s_cbranch_scc1 .LBB0_587
	s_cmpk_lt_i32 s45, 0x380
	s_mov_b64 s[28:29], -1
	s_cbranch_scc1 .LBB0_581
	s_cmpk_lt_u32 s45, 0x580
	s_cbranch_scc1 .LBB0_574
	s_cmpk_lt_u32 s45, 0x980
	s_cbranch_scc1 .LBB0_569
	s_cmpk_lt_u32 s45, 0xf00
	s_mov_b64 s[0:1], -1
	s_cbranch_scc1 .LBB0_567
	v_readlane_b32 s0, v254, 56
	v_readlane_b32 s1, v254, 57
	s_load_dwordx2 s[2:3], s[0:1], 0xf0
	v_readlane_b32 s0, v255, 0
	s_add_i32 s0, s0, s36
	s_and_b32 s0, s0, 0x7fffffc0
	v_readlane_b32 s1, v255, 1
	s_add_i32 s27, s0, 0xffffc400
	s_add_i32 s0, s39, s33
	s_and_b32 s26, s0, 0x3c0
	s_mov_b64 s[0:1], 0

.LBB0_587:
	v_readlane_b32 s0, v254, 62
	s_mul_i32 s46, s0, 3
	s_add_i32 s46, s46, s43
	s_cmp_lt_i32 s46, s32
	s_cselect_b64 s[26:27], -1, 0
	s_cmp_ge_i32 s46, s32
	v_readlane_b32 s1, v254, 63
	s_cbranch_scc1 .LBB0_613
	s_cmpk_lt_i32 s46, 0x380
	s_mov_b64 s[30:31], -1
	s_cbranch_scc1 .LBB0_607
	s_cmpk_lt_u32 s46, 0x580
	s_cbranch_scc1 .LBB0_600
	s_cmpk_lt_u32 s46, 0x980
	s_cbranch_scc1 .LBB0_595
	s_cmpk_lt_u32 s46, 0xf00
	s_mov_b64 s[0:1], -1
	s_cbranch_scc1 .LBB0_593
	v_readlane_b32 s0, v254, 56
	v_readlane_b32 s1, v254, 57
	s_load_dwordx2 s[2:3], s[0:1], 0xf0
	s_add_i32 s0, s41, s36
	s_and_b32 s0, s0, 0x7fffffc0
	s_add_i32 s29, s0, 0xffffc400
	s_add_i32 s0, s40, s33
	s_and_b32 s28, s0, 0x3c0
	s_mov_b64 s[0:1], 0

.LBB0_716:
	s_mov_b32 s32, 0
	s_mov_b64 s[0:1], -1

.LBB0_1293:
	s_mov_b32 s32, 0
	s_cmp_lg_u32 s70, 12
	s_cbranch_scc1 .Ltd_skip
	v_readlane_b32 s0, v254, 62
	s_cmpk_lg_u32 s0, 0x100
	s_cbranch_scc1 .Ltd_skip
	v_readlane_b32 s0, v255, 2
	s_cmpk_lt_u32 s0, 0xac
	s_cbranch_scc1 .Ltd_skip
	s_add_i32 s32, s0, 0xe54
	v_readlane_b32 s0, v254, 56
	v_readlane_b32 s1, v254, 57
	s_load_dwordx2 s[18:19], s[0:1], 0x108
	v_ashrrev_i32_e32 v1, 4, v174
	s_waitcnt vmcnt(0) lgkmcnt(0)
.Ltd_BB0_506:
	s_mov_b32 s0, s32
	s_cmpk_gt_i32 s0, 0x11bf
	s_waitcnt lgkmcnt(0)
	s_barrier
	v_readlane_b32 s1, v255, 3
	s_cbranch_scc1 .Ltd_end
	s_add_u32 s6, s18, 0x1e80000
	s_addc_u32 s7, s19, 0
	s_add_u32 s8, s18, 0x1380000
	s_addc_u32 s9, s19, 0
	s_add_u32 s10, s18, 0x1bd3d800
	v_ashrrev_i32_e32 v27, 3, v174
	v_lshlrev_b32_e32 v2, 3, v174
	s_addc_u32 s11, s19, 0
	s_waitcnt vmcnt(0)
	v_and_b32_e32 v36, 56, v2
	v_lshlrev_b32_e32 v2, 2, v174
	s_add_u32 s12, s18, 0x780000
	v_lshlrev_b32_e32 v4, 1, v27
	v_lshrrev_b32_e32 v5, 2, v27
	s_movk_i32 s0, 0x54
	v_and_b32_e32 v2, 60, v2
	s_addc_u32 s13, s19, 0
	v_and_b32_e32 v4, 24, v4
	v_and_b32_e32 v5, 4, v5
	v_and_b32_e32 v6, 35, v27
	v_readlane_b32 s1, v254, 63
	s_mov_b32 s2, s0
	s_lshl_b32 s34, s0, 2
	s_movk_i32 s0, 0x104
	v_lshl_add_u32 v3, v2, 2, 0
	v_or3_b32 v37, v5, v6, v4
	v_mul_lo_u32 v4, v1, s0
	v_mad_u32_u24 v48, v36, s0, 0
	s_mov_b32 s0, s32
	s_lshl_b32 s33, s0, 6
	s_lshl_b32 s35, s2, 8
	s_lshl_b32 s36, s0, 2
	s_lshl_b32 s37, s2, 4
	s_lshl_b32 s38, s2, 1
	s_lshl_b32 s39, s2, 7
	s_mul_i32 s40, s2, 0xc0
	s_mul_i32 s41, s2, 12
	s_lshl_b32 s42, s2, 6
	s_waitcnt vmcnt(12)
	v_lshlrev_b32_e32 v38, 2, v2
	v_add_u32_e32 v49, v3, v4
	s_mov_b32 s43, s0
	v_readlane_b32 s1, v255, 3
	s_branch .Ltd_BB0_510

.Ltd_BB0_535:
	s_movk_i32 s0, 0x54
	s_add_i32 s44, s0, s43
	s_cmpk_lt_i32 s44, 0x11c0
	s_cselect_b64 s[22:23], -1, 0
	s_cmpk_gt_i32 s44, 0x11bf
	v_readlane_b32 s1, v254, 63
	s_cbranch_scc1 .Ltd_BB0_561
	s_cmpk_lt_i32 s44, 0x380
	s_mov_b64 s[26:27], -1
	s_cbranch_scc1 .Ltd_BB0_555
	s_cmpk_lt_u32 s44, 0x580
	s_cbranch_scc1 .Ltd_BB0_548
	s_cmpk_lt_u32 s44, 0x980
	s_cbranch_scc1 .Ltd_BB0_543
	s_cmpk_lt_u32 s44, 0xf00
	s_mov_b64 s[0:1], -1
	s_cbranch_scc1 .Ltd_BB0_541
	v_readlane_b32 s0, v254, 56
	v_readlane_b32 s1, v254, 57
	s_load_dwordx2 s[2:3], s[0:1], 0xf0
	s_add_i32 s0, s34, s36
	s_and_b32 s0, s0, 0x7fffffc0
	s_add_i32 s25, s0, 0xffffc400
	s_add_i32 s0, s42, s33
	s_and_b32 s24, s0, 0x3c0
	s_mov_b64 s[0:1], 0

.Ltd_BB0_561:
	s_add_i32 s45, s38, s43
	s_cmpk_lt_i32 s45, 0x11c0
	s_cselect_b64 s[24:25], -1, 0
	s_cmpk_gt_i32 s45, 0x11bf
	s_cbranch_scc1 .Ltd_BB0_587
	s_cmpk_lt_i32 s45, 0x380
	s_mov_b64 s[28:29], -1
	s_cbranch_scc1 .Ltd_BB0_581
	s_cmpk_lt_u32 s45, 0x580
	s_cbranch_scc1 .Ltd_BB0_574
	s_cmpk_lt_u32 s45, 0x980
	s_cbranch_scc1 .Ltd_BB0_569
	s_cmpk_lt_u32 s45, 0xf00
	s_mov_b64 s[0:1], -1
	s_cbranch_scc1 .Ltd_BB0_567
	v_readlane_b32 s0, v254, 56
	v_readlane_b32 s1, v254, 57
	s_load_dwordx2 s[2:3], s[0:1], 0xf0
	s_movk_i32 s0, 0x2a0
	s_add_i32 s0, s0, s36
	s_and_b32 s0, s0, 0x7fffffc0
	v_readlane_b32 s1, v255, 1
	s_add_i32 s27, s0, 0xffffc400
	s_add_i32 s0, s39, s33
	s_and_b32 s26, s0, 0x3c0
	s_mov_b64 s[0:1], 0

.Ltd_BB0_572:
	s_nop 0
	s_load_dwordx2 s[2:3], s[2:3], 0x0
	s_movk_i32 s4, 0x2a0
	s_add_i32 s4, s4, s36
	s_addk_i32 s4, 0xea00
	v_readlane_b32 s5, v255, 1
	s_and_b32 s27, s4, 0x3c0
	s_add_i32 s4, s39, s33
	s_and_b32 s26, s4, 0x3c0
	s_mov_b64 s[4:5], 0x400

.Ltd_BB0_587:
	s_movk_i32 s0, 0x54
	s_mul_i32 s46, s0, 3
	s_add_i32 s46, s46, s43
	s_cmpk_lt_i32 s46, 0x11c0
	s_cselect_b64 s[26:27], -1, 0
	s_cmpk_gt_i32 s46, 0x11bf
	v_readlane_b32 s1, v254, 63
	s_cbranch_scc1 .Ltd_BB0_613
	s_cmpk_lt_i32 s46, 0x380
	s_mov_b64 s[30:31], -1
	s_cbranch_scc1 .Ltd_BB0_607
	s_cmpk_lt_u32 s46, 0x580
	s_cbranch_scc1 .Ltd_BB0_600
	s_cmpk_lt_u32 s46, 0x980
	s_cbranch_scc1 .Ltd_BB0_595
	s_cmpk_lt_u32 s46, 0xf00
	s_mov_b64 s[0:1], -1
	s_cbranch_scc1 .Ltd_BB0_593
	v_readlane_b32 s0, v254, 56
	v_readlane_b32 s1, v254, 57
	s_load_dwordx2 s[2:3], s[0:1], 0xf0
	s_add_i32 s0, s41, s36
	s_and_b32 s0, s0, 0x7fffffc0
	s_add_i32 s29, s0, 0xffffc400
	s_add_i32 s0, s40, s33
	s_and_b32 s28, s0, 0x3c0
	s_mov_b64 s[0:1], 0

.Ltd_BB0_658:
	s_cmpk_lt_i32 s45, 0x380
	s_cbranch_scc1 .Ltd_BB0_673
	s_cmpk_lt_u32 s45, 0x580
	s_mov_b64 s[14:15], -1
	s_cbranch_scc1 .Ltd_BB0_669
	s_cmpk_lt_u32 s45, 0x980
	s_cbranch_scc1 .Ltd_BB0_666
	s_cmpk_lt_u32 s45, 0xf00
	s_mov_b64 s[2:3], -1
	s_cbranch_scc1 .Ltd_BB0_663
	s_movk_i32 s2, 0x2a0
	s_add_i32 s2, s2, s36
	s_and_b32 s2, s2, 0x7fffffc0
	v_readlane_b32 s3, v255, 1
	s_add_i32 s22, s2, 0xffffc400
	s_add_i32 s2, s39, s33
	s_and_b32 s23, s2, 0x3c0
	s_mov_b64 s[2:3], 0

.Ltd_BB0_666:
	s_andn2_b64 vcc, exec, s[14:15]
	v_mov_b32_e32 v28, v37
	s_cbranch_vccnz .Ltd_BB0_668
	s_add_i32 s2, s45, 0xfffffa80
	s_lshr_b32 s14, s2, 8
	s_cmpk_gt_u32 s2, 0xff
	s_cselect_b64 s[4:5], -1, 0
	s_cmp_eq_u32 s14, 2
	s_mov_b32 s2, 0xf80000
	s_cselect_b32 s2, s2, 0x1180000
	s_cmp_lg_u32 s14, 1
	s_cselect_b32 s15, s2, 0xd80000
	s_and_b64 s[2:3], s[4:5], exec
	s_cselect_b32 s2, s15, 0xb80000
	s_add_u32 s2, s18, s2
	s_movk_i32 s22, 0x2a0
	s_addc_u32 s3, s19, 0
	s_add_i32 s15, s22, s36
	s_addk_i32 s15, 0xea00
	v_readlane_b32 s23, v255, 1
	s_and_b32 s22, s15, 0x3c0
	s_add_i32 s15, s39, s33
	s_and_b32 s23, s15, 0x3c0
	s_cmp_lg_u32 s14, 3
	s_cselect_b64 s[14:15], -1, 0
	s_and_b64 vcc, s[4:5], s[14:15]
	v_cndmask_b32_e32 v28, v37, v27, vcc
	s_mov_b64 s[4:5], 0x400

.Ltd_BB0_669:
	s_andn2_b64 vcc, exec, s[14:15]
	s_cbranch_vccnz .Ltd_BB0_686
	s_movk_i32 s4, 0x2a0
	s_add_i32 s3, s4, s36
	s_addk_i32 s3, 0xf200
	s_add_i32 s2, s45, 0xfffffc80
	v_readlane_b32 s5, v255, 1
	s_and_b32 s14, s3, 0x7fffffc0
	s_cmpk_lt_u32 s2, 0x100
	s_mov_b64 s[4:5], 0x800
	s_cbranch_scc1 .Ltd_BB0_684
	s_addk_i32 s14, 0xfc00
	s_mov_b64 s[4:5], 0x400
	v_mov_b32_e32 v28, v27
	s_mov_b64 s[2:3], s[10:11]
	s_branch .Ltd_BB0_685

.Ltd_BB0_714:
	s_andn2_b64 vcc, exec, s[4:5]
	s_cbranch_vccnz .Ltd_BB0_508
	s_waitcnt lgkmcnt(3)
	v_cvt_pk_bf16_f32 v28, v46, v47
	s_waitcnt lgkmcnt(2)
	v_cvt_pk_bf16_f32 v29, v44, v45
	s_waitcnt lgkmcnt(1)
	v_cvt_pk_bf16_f32 v30, v42, v43
	s_waitcnt lgkmcnt(0)
	v_cvt_pk_bf16_f32 v31, v40, v41
	s_branch .Ltd_BB0_508
.Ltd_end:
	s_mov_b32 s32, 0
